# stagger: odd blockIdx groups start P1 and P6 16us later (epilogue memory phases beside the other half's MFMA loops)
# speedup vs baseline: 1.0100x; 1.0049x over previous
; #define PG8_STAGE(bufoff, gbase, voff) do { const int _so = (int)((const char*)(gbase) - base_##voff); _Pragma("unroll") for (int _i = 0; _i < 2; ++_i) \
;         __builtin_amdgcn_raw_ptr_buffer_load_lds(rsrc_##voff, (PG8_LAS unsigned*)(lds + (bufoff) + ldsw + _i * 8192), 16, (int)(voff)[_i], _so, 0, 0); } while (0)
; #define PG8_WAIT_V(n) asm volatile("s_waitcnt vmcnt(" #n ")" ::: "memory")
; #define PG8_BAR __builtin_amdgcn_s_barrier()
;     __host__ __device__ bool next(int i, Unit& u) const {
;         const long L = (long)i * G + c; if (L >= nwg) return false;
;         int wgid = (int)L; { const int q = nwg / NXCD, r = nwg % NXCD, xcd = wgid % NXCD, off = wgid / NXCD; wgid = (xcd < r ? xcd * (q + 1) : r * (q + 1) + (xcd - r) * q) + off; }
;         const int nig = WGM * nN, gid = wgid / nig, fm = gid * WGM, gsz = (nM - fm) < WGM ? (nM - fm) : WGM;
;         u.pm = fm + ((wgid % nig) % gsz); u.pn = (wgid % nig) / gsz; return true;
; template <class Epi, class Sched, bool ALIGN_EPI = false, bool SP2 = false>
; __device__ __forceinline__ void gemm_phase(PG8_LAS unsigned char* lds, const Gemm g, const Sched& S, const Epi& E) {
;     ...
;     const char* cA = (const char*)g.A + (size_t)cur.pm * tstep; const char* cB = (const char*)g.Bt + (size_t)cur.pn * tstep;
;     S.a_ready(cur);
;     if constexpr (SP2) {
;         PG8_STAGE(PG8_SB(0, 0), cB, voffB); PG8_STAGE(PG8_SB(0, 1), cB + hstep, voffB); PG8_STAGE(PG8_SA(0, 0), cA, voffA); PG8_STAGE(PG8_SA(0, 1), cA + hstep, voffA);
;         if (wr == 1) PG8_BAR;
;         PG8_WAIT_V(2); PG8_BAR;
;         PG8_STAGE(PG8_SB(1, 0), cB + kstep, voffB); PG8_STAGE(PG8_SA(1, 0), cA + kstep, voffA); PG8_STAGE(PG8_SB(1, 1), cB + hstep + kstep, voffB);
.LBB0_105:
	s_or_b64 exec, exec, s[4:5]
	s_waitcnt lgkmcnt(0)
	s_barrier
	v_readlane_b32 s2, v254, 4
	v_readlane_b32 s3, v254, 5
	v_lshlrev_b32_e32 v0, 2, v188
	s_nop 4
	global_load_dword v1, v0, s[2:3] sc1
	s_waitcnt vmcnt(0)
	v_add_u32_e32 v2, -1, v1
	v_and_b32_e32 v2, v2, v1
	v_cmp_eq_u32_e32 vcc, 0, v2
	v_cmp_ne_u32_e64 s[4:5], 0, v1
	s_and_b64 s[4:5], vcc, s[4:5]
	s_cmp_eq_u64 s[4:5], exec
	s_cselect_b32 s2, 1, 0
	v_mov_b32_e32 v0, s2
	v_mov_b32_e32 v1, 0x20430
	ds_write_b32 v1, v0
	s_cmp_eq_u32 s2, 0
	s_cbranch_scc1 .Lstag0_end
	v_readlane_b32 s3, v255, 0
	s_bitcmp1_b32 s3, 0
	s_cbranch_scc0 .Lstag0_end
	s_memrealtime s[4:5]
	s_waitcnt lgkmcnt(0)
.Lstag0_loop:
	s_sleep 8
	s_memrealtime s[2:3]
	s_waitcnt lgkmcnt(0)
	s_sub_u32 s2, s2, s4
	s_cmp_lt_u32 s2, 1600
	s_cbranch_scc1 .Lstag0_loop
.Lstag0_end:
.LBB0_106:
	v_readlane_b32 s2, v254, 0
	v_readlane_b32 s3, v254, 1
	s_cmp_lt_i32 s2, 2
	s_cselect_b64 s[2:3], -1, 0
	s_add_u32 s40, s90, 0xf500000
	s_addc_u32 s7, s91, 0
	s_mov_b32 s6, s40
	s_and_b64 s[4:5], s[2:3], s[0:1]
	v_writelane_b32 v255, s6, 6
	s_andn2_b64 vcc, exec, s[4:5]
	s_nop 0
	v_writelane_b32 v255, s7, 7
	s_cbranch_vccnz .LBB0_123
	s_cmpk_gt_i32 s66, 0xaff
	v_readfirstlane_b32 s1, v189
	s_cbranch_scc1 .LBB0_123
	v_lshlrev_b32_e32 v1, 4, v189
	v_and_b32_e32 v0, 32, v189
	v_bitop3_b32 v0, v1, v0, 48 bitop3:0x6c
	v_and_or_b32 v3, v189, 64, v0
	v_lshrrev_b32_e32 v0, 1, v189
	v_lshrrev_b32_e32 v4, 5, v189
	v_and_b32_e32 v0, 24, v0
	v_and_b32_e32 v4, 4, v4
	v_bfe_u32 v5, v189, 2, 2
	v_bfe_u32 v2, v189, 2, 4
	v_or3_b32 v4, v4, v5, v0
	v_lshrrev_b32_e32 v5, 3, v189
	s_movk_i32 s0, 0x70
	v_readlane_b32 s2, v254, 44
	v_and_or_b32 v6, v5, s0, v2
	s_movk_i32 s0, 0x60
	v_add_u32_e32 v1, 0x2000, v1
	v_readlane_b32 s3, v254, 45
	v_and_or_b32 v5, v5, s0, v4
	v_lshrrev_b32_e32 v1, 7, v1
	s_movk_i32 s0, 0xf0
	s_and_b32 s25, s3, 0xffff
	v_readlane_b32 s2, v254, 46
	v_and_or_b32 v2, v1, s0, v2
	s_movk_i32 s0, 0xe0
	s_ashr_i32 s2, s66, 31
	v_and_or_b32 v1, v1, s0, v4
	s_lshr_b32 s0, s2, 29
	s_add_i32 s0, s66, s0
	s_lshr_b32 s33, s1, 6
	v_readlane_b32 s3, v254, 47
	s_ashr_i32 s6, s0, 3
	s_and_b32 s0, s0, -8
	s_lshr_b32 s23, s1, 8
	s_lshl_b32 s8, s33, 10
	s_and_b32 s29, s3, 0xffff
	s_sub_i32 s0, s66, s0
	s_cmp_lt_i32 s0, 0
	s_movk_i32 s3, 0x161
	s_cselect_b32 s7, s3, 0x160
	s_mul_i32 s0, s0, s7
	s_add_i32 s0, s0, s6
	s_mul_hi_i32 s6, s0, 0x2e8ba2e9
	s_lshr_b32 s7, s6, 31
	s_ashr_i32 s6, s6, 6
	s_add_i32 s6, s6, s7
	s_lshl_b32 s7, s6, 3
	s_mulk_i32 s6, 0x160
	s_sub_i32 s6, s0, s6
	s_sext_i32_i16 s0, s6
	s_bfe_u32 s0, s0, 0x3001c
	s_add_i32 s9, s6, s0
	s_sext_i32_i16 s0, s9
	s_and_b32 s9, s9, 0xfff8
	s_sub_i32 s6, s6, s9
	s_lshr_b32 s0, s0, 3
	s_sext_i32_i16 s6, s6
	s_add_i32 s8, s8, 0
	s_mov_b32 s27, 0x20000
	s_mov_b32 s26, 0x7ffffff0
	s_add_i32 s64, s7, s6
	s_bfe_i64 s[6:7], s[0:1], 0x100000
	s_add_i32 s9, s8, 0x10000
	v_lshl_or_b32 v137, v5, 12, v3
	s_mov_b32 s30, s26
	s_mov_b32 s31, s27
	s_lshl_b64 s[38:39], s[6:7], 20
	s_mov_b32 m0, s9
	s_add_i32 s10, s8, 0x12000
	v_lshl_or_b32 v139, v1, 12, v3
	buffer_load_dwordx4 v137, s[28:31], s38 offen lds
	s_mov_b32 m0, s10
	s_add_i32 s11, s8, 0x14000
	buffer_load_dwordx4 v139, s[28:31], s38 offen lds
	s_or_b32 s6, s38, 0x80000
	s_mov_b32 m0, s11
	s_add_i32 s12, s8, 0x16000
	s_ashr_i32 s65, s64, 31
	buffer_load_dwordx4 v137, s[28:31], s6 offen lds
	s_mov_b32 m0, s12
	v_lshl_or_b32 v136, v6, 12, v3
	s_lshl_b64 s[42:43], s[64:65], 20
	buffer_load_dwordx4 v139, s[28:31], s6 offen lds
	s_mov_b32 m0, s8
	s_add_i32 s13, s8, 0x2000
	v_lshl_or_b32 v138, v2, 12, v3
	buffer_load_dwordx4 v136, s[24:27], s42 offen lds
	s_mov_b32 m0, s13
	s_add_i32 s14, s8, 0x4000
	buffer_load_dwordx4 v138, s[24:27], s42 offen lds
	s_or_b32 s6, s42, 0x80000
	s_mov_b32 m0, s14
	s_add_i32 s15, s8, 0x6000
	buffer_load_dwordx4 v136, s[24:27], s6 offen lds
	s_mov_b32 m0, s15
	s_cmp_eq_u32 s23, 1
	buffer_load_dwordx4 v138, s[24:27], s6 offen lds
	s_cselect_b64 s[6:7], -1, 0
	s_cmp_lg_u32 s23, 1
	s_mov_b32 s16, 0
	s_cbranch_scc1 .LBB0_110
	s_barrier

; #define SEAM(k) do { if (IN(k) && IN((k) + 1)) xcd_barrier(bar); } while (0)
; __global__ void __launch_bounds__(NWAVES * 64, 2) hybrid_fwd(Args args) {
;     ...
;         }
;         __syncthreads();
;     }
;     SEAM(5);
;     if (IN(6)) {
;         { pg8::Gemm g{Qb, (const bf16*)(ws + WS_PA), M, D, AW}; pg8::StaticOrder S; S.init(M, D, G, (int)blockIdx.x);
.LBB0_463:
	s_or_b64 exec, exec, s[4:5]
	s_waitcnt lgkmcnt(0)
	s_barrier
	v_mov_b32_e32 v0, 0x20430
	ds_read_b32 v0, v0
	s_waitcnt lgkmcnt(0)
	v_readfirstlane_b32 s2, v0
	s_cmp_eq_u32 s2, 0
	s_cbranch_scc1 .Lstag1_end
	v_readlane_b32 s3, v255, 0
	s_bitcmp1_b32 s3, 0
	s_cbranch_scc0 .Lstag1_end
	s_memrealtime s[4:5]
	s_waitcnt lgkmcnt(0)

; template <class Epi, class Sched, bool ALIGN_EPI = false, bool SP2 = false>
; __device__ __forceinline__ void gemm_phase(PG8_LAS unsigned char* lds, const Gemm g, const Sched& S, const Epi& E) {
;     const int tid = threadIdx.x, wid = __builtin_amdgcn_readfirstlane(tid >> 6), lane = tid & 63, wr = wid >> 2, wc = wid & 3, fr = lane & 15, fq = lane >> 4;
;     const int K = g.K, nt = K / BK;
;     unsigned voffA[2], voffB[2];
; #pragma unroll
;     for (int i = 0; i < 2; ++i) { int R, C; stage_rc(tid * 16 + i * 8192, R, C); const int Rb = Epi::PERM ? ((R & ~31) + perm32(R & 31)) : R;
;         voffA[i] = (unsigned)(R * K + C) * 2u; voffB[i] = (unsigned)(Rb * K + C) * 2u; }
;     const size_t kstep = (size_t)(BK * 2);
;     const size_t hstep = (size_t)HALF * K * 2;
;     const size_t tstep = 2 * hstep;
;     const unsigned ldsw = (unsigned)wid * 1024u;
;     const int aoff = lds_byte(wr * 64 + fr, fq * 8), boff = lds_byte(wc * 32 + fr, fq * 8);
; __global__ void __launch_bounds__(NWAVES * 64, 2) hybrid_fwd(Args args) {
;     ...
;         { pg8::Gemm g{Qb, (const bf16*)(ws + WS_PA), M, D, AW}; pg8::StaticOrder S; S.init(M, D, G, (int)blockIdx.x);
;           pg8::EpiGate<false> E{Gb, Tb}; pg8::gemm_phase<pg8::EpiGate<false>, pg8::StaticOrder, true, true>(lds, g, S, E); }
.Lstag1_end:
.LBB0_464:
	s_cmp_lt_i32 s74, 7
	s_cselect_b64 s[2:3], -1, 0
	s_and_b64 s[8:9], s[2:3], s[0:1]
	s_andn2_b64 vcc, exec, s[8:9]
	v_lshrrev_b32_e32 v196, 1, v189
	s_cbranch_vccnz .LBB0_513
	v_lshrrev_b32_e32 v3, 5, v189
	v_lshrrev_b32_e32 v5, 1, v189
	v_and_b32_e32 v3, 4, v3
	v_bfe_u32 v4, v189, 2, 2
	s_waitcnt lgkmcnt(13)
	v_and_b32_e32 v138, 24, v5
	v_lshlrev_b32_e32 v0, 4, v189
	v_and_b32_e32 v1, 32, v189
	v_bfe_u32 v2, v189, 2, 4
	v_or3_b32 v3, v3, v4, v138
	v_lshrrev_b32_e32 v4, 3, v189
	s_movk_i32 s0, 0x70
	v_bitop3_b32 v1, v0, v1, 48 bitop3:0x6c
	v_and_or_b32 v5, v4, s0, v2
	s_movk_i32 s0, 0x60
	v_add_u32_e32 v0, 0x2000, v0
	v_and_or_b32 v4, v4, s0, v3
	v_lshrrev_b32_e32 v0, 7, v0
	s_movk_i32 s0, 0xf0
	v_and_or_b32 v2, v0, s0, v2
	s_movk_i32 s0, 0xe0
	v_and_or_b32 v1, v189, 64, v1
	v_and_or_b32 v0, v0, s0, v3
	s_waitcnt lgkmcnt(5)
	v_lshl_or_b32 v176, v5, 11, v1
	s_waitcnt lgkmcnt(4)
	v_lshl_or_b32 v177, v4, 11, v1
	v_lshl_or_b32 v178, v2, 11, v1
	v_lshl_or_b32 v179, v0, 11, v1
	v_lshlrev_b32_e32 v0, 6, v189
	v_lshlrev_b32_e32 v1, 2, v189
	v_lshlrev_b32_e32 v140, 1, v138
	v_and_b32_e32 v0, 0x3c0, v0
	v_and_b32_e32 v1, 32, v1
	s_cmpk_lt_i32 s66, 0x200
	v_readfirstlane_b32 s26, v189
	v_and_b32_e32 v139, 15, v189
	s_cselect_b64 s[10:11], -1, 0
	s_cmpk_gt_i32 s66, 0x1ff
	v_bitop3_b32 v141, v140, v1, v0 bitop3:0x36
	s_cbranch_scc1 .LBB0_489
	s_ashr_i32 s2, s66, 31
	s_lshr_b32 s0, s2, 29
	s_add_i32 s3, s66, s0
	s_and_b32 s0, s3, -8
	s_sub_i32 s4, s66, s0
	s_cmp_gt_i32 s4, -1
	s_cbranch_scc0 .LBB0_468
	s_lshl_b32 s12, s4, 6
	s_cbranch_execz .LBB0_469
	s_branch .LBB0_470
